# attention phase: one static s_setprio 1 for waves 4-7 (second query half) for the whole phase, reset at the end; on top of v94
# speedup vs baseline: 1.0130x; 1.0130x over previous
.LBB0_1179:
	s_or_b64 exec, exec, s[2:3]
	s_waitcnt lgkmcnt(0)
	s_barrier
	s_getreg_b32 s0, hwreg(HW_REG_HW_ID, 0, 6)
	s_and_b32 s0, s0, 63
	s_lshl_b32 s0, s0, 2
	s_add_i32 s0, s0, 0
	s_add_i32 s0, s0, 0x22ef0
	v_mov_b32_e32 v0, s0
	ds_read_b32 v0, v0
	v_mov_b32_e32 v1, v177
	v_readlane_b32 s2, v253, 1
	v_readlane_b32 s3, v253, 2
	s_waitcnt lgkmcnt(0)
	v_readfirstlane_b32 s0, v0
	v_mbcnt_lo_u32_b32 v0, -1, v1
	v_mbcnt_hi_u32_b32 v0, -1, v0
	v_lshl_add_u32 v0, s0, 6, v0
	s_cmp_ge_u32 s0, 4
	s_cbranch_scc0 .Lattn_prio_done
	s_setprio 1
.Lattn_prio_done:
	s_mov_b32 s0, 13
	s_ashr_i32 s1, s0, 31
	s_lshl_b64 s[0:1], s[0:1], 3
	s_add_u32 s0, s2, s0
	s_addc_u32 s1, s3, s1
	s_load_dwordx2 s[0:1], s[0:1], 0x0
	s_lshl_b32 s2, s55, 2
	v_and_b32_e32 v1, 63, v0
	v_lshlrev_b32_e32 v2, 2, v1
	v_cmp_lt_i32_e32 vcc, v231, v230
	s_waitcnt lgkmcnt(0)
	s_add_u32 s0, s0, s2
	s_addc_u32 s1, s1, 0
	global_load_dword v3, v2, s[0:1] offset:256
	global_load_dword v4, v2, s[0:1] offset:512
	s_nop 0
	global_load_dword v2, v2, s[0:1] offset:768
	v_cndmask_b32_e32 v5, v229, v231, vcc
	v_lshlrev_b32_e32 v5, 2, v5
	v_cmp_lt_i32_e32 vcc, v232, v230
	v_readlane_b32 s18, v253, 27
	v_readlane_b32 s19, v253, 28
	v_cndmask_b32_e32 v6, v229, v232, vcc
	v_lshlrev_b32_e32 v6, 2, v6
	v_cmp_lt_i32_e32 vcc, v233, v230
	s_mov_b64 s[2:3], 0x8800000
	s_mov_b64 s[4:5], 0xba00000
	v_cndmask_b32_e32 v7, v229, v233, vcc
	v_lshlrev_b32_e32 v7, 2, v7
	v_cmp_lt_i32_e32 vcc, v234, v230
	s_mov_b64 s[6:7], 0xc200000
	s_mov_b64 s[8:9], 0xca00000
	v_cndmask_b32_e32 v8, v229, v234, vcc
	v_lshlrev_b32_e32 v8, 2, v8
	v_cmp_lt_i32_e32 vcc, v235, v230
	s_mov_b64 s[10:11], 0xd200000
	s_mov_b64 s[12:13], 0xe200000
	v_cndmask_b32_e32 v9, v229, v235, vcc
	v_lshlrev_b32_e32 v9, 2, v9
	v_cmp_lt_i32_e32 vcc, v236, v230
	s_mov_b64 s[0:1], 0xe300000
	s_mov_b64 s[14:15], 0xda00000
	v_cndmask_b32_e32 v10, v229, v236, vcc
	v_lshlrev_b32_e32 v10, 2, v10
	s_andn2_b64 vcc, exec, s[18:19]
	s_mov_b64 s[16:17], 0xe400000
	v_readfirstlane_b32 s24, v0
	s_waitcnt vmcnt(2)
	v_and_b32_e32 v11, 0x7fffffff, v3
	s_waitcnt vmcnt(1)
	v_and_b32_e32 v12, 0x7fffffff, v4
	s_waitcnt vmcnt(0)
	v_and_b32_e32 v13, 0x7fffffff, v2
	ds_bpermute_b32 v12, v5, v12
	ds_bpermute_b32 v11, v5, v11
	ds_bpermute_b32 v5, v5, v13
	v_max_f32_e64 v4, |v4|, |v4|
	v_max_f32_e64 v3, |v3|, |v3|
	s_waitcnt lgkmcnt(2)
	v_max_f32_e32 v12, v12, v12
	v_max_f32_e64 v2, |v2|, |v2|
	s_waitcnt lgkmcnt(1)
	v_max_f32_e32 v11, v11, v11
	s_waitcnt lgkmcnt(0)
	v_max_f32_e32 v5, v5, v5
	v_max_f32_e32 v4, v4, v12
	v_max_f32_e32 v3, v3, v11
	v_max_f32_e32 v2, v2, v5
	ds_bpermute_b32 v11, v6, v4
	ds_bpermute_b32 v5, v6, v3
	ds_bpermute_b32 v6, v6, v2
	s_waitcnt lgkmcnt(2)
	v_max_f32_e32 v11, v11, v11
	s_waitcnt lgkmcnt(1)
	v_max_f32_e32 v5, v5, v5
	s_waitcnt lgkmcnt(0)
	v_max_f32_e32 v6, v6, v6
	v_max_f32_e32 v4, v4, v11
	v_max_f32_e32 v3, v3, v5
	v_max_f32_e32 v2, v2, v6
	ds_bpermute_b32 v6, v7, v4
	ds_bpermute_b32 v5, v7, v3
	ds_bpermute_b32 v7, v7, v2
	s_waitcnt lgkmcnt(2)
	v_max_f32_e32 v6, v6, v6
	v_max_f32_e32 v4, v4, v6
	s_waitcnt lgkmcnt(0)
	v_max_f32_e32 v7, v7, v7
	v_max_f32_e32 v5, v5, v5
	v_max_f32_e32 v2, v2, v7
	ds_bpermute_b32 v6, v8, v4
	v_max_f32_e32 v3, v3, v5
	ds_bpermute_b32 v7, v8, v2
	ds_bpermute_b32 v5, v8, v3
	s_waitcnt lgkmcnt(2)
	v_max_f32_e32 v6, v6, v6
	v_max_f32_e32 v4, v4, v6
	s_waitcnt lgkmcnt(1)
	v_max_f32_e32 v7, v7, v7
	s_waitcnt lgkmcnt(0)
	v_max_f32_e32 v5, v5, v5
	v_max_f32_e32 v2, v2, v7
	ds_bpermute_b32 v6, v9, v4
	v_max_f32_e32 v3, v3, v5
	ds_bpermute_b32 v7, v9, v2
	ds_bpermute_b32 v5, v9, v3
	s_waitcnt lgkmcnt(2)
	v_max_f32_e32 v6, v6, v6
	v_max_f32_e32 v4, v4, v6
	s_waitcnt lgkmcnt(1)
	v_max_f32_e32 v7, v7, v7
	s_waitcnt lgkmcnt(0)
	v_max_f32_e32 v5, v5, v5
	v_max_f32_e32 v2, v2, v7
	ds_bpermute_b32 v6, v10, v4
	v_max_f32_e32 v3, v3, v5
	ds_bpermute_b32 v7, v10, v2
	ds_bpermute_b32 v5, v10, v3
	s_waitcnt lgkmcnt(2)
	v_max_f32_e32 v6, v6, v6
	v_max_f32_e32 v4, v4, v6
	s_waitcnt lgkmcnt(1)
	v_max_f32_e32 v7, v7, v7
	s_waitcnt lgkmcnt(0)
	v_max_f32_e32 v5, v5, v5
	v_max_f32_e32 v2, v2, v7
	v_readfirstlane_b32 s18, v4
	v_max_f32_e32 v3, v3, v5
	s_nop 0
	v_writelane_b32 v255, s18, 3
	v_readfirstlane_b32 s18, v2
	v_readfirstlane_b32 s42, v3
	s_nop 0
	v_writelane_b32 v255, s18, 5
	s_cbranch_vccnz .LBB0_1317
	s_mov_b64 s[22:23], s[66:67]
	s_bfe_u32 s66, s24, 0x20006
	s_add_u32 s18, s22, s2
	s_addc_u32 s19, s23, s3
	s_add_u32 s46, s22, s4
	s_addc_u32 s47, s23, s5
	s_add_u32 s37, s22, s6
	s_addc_u32 s65, s23, s7
	s_add_u32 s30, s22, s8
	s_addc_u32 s3, s23, s9
	s_add_u32 s2, s22, s10
	v_writelane_b32 v255, s2, 7
	s_addc_u32 s2, s23, s11
	v_writelane_b32 v255, s2, 9
	s_add_u32 s2, s22, s12
	v_writelane_b32 v255, s2, 10
	s_addc_u32 s2, s23, s13
	v_writelane_b32 v255, s2, 11
	s_add_u32 s2, s22, s0
	v_writelane_b32 v255, s2, 12
	s_addc_u32 s2, s23, s1
	s_add_u32 s20, s22, s14
	s_addc_u32 s21, s23, s15
	s_add_u32 s22, s22, s16
	v_writelane_b32 v255, s2, 14
	s_addc_u32 s23, s23, s17
	v_lshlrev_b32_e32 v3, 2, v0
	v_readlane_b32 s2, v254, 40
	s_ashr_i32 s14, s24, 3
	v_mov_b32_e32 v2, s14
	v_add_u32_e32 v157, s2, v3
	s_movk_i32 s2, 0xffe0
	s_cmp_eq_u32 s66, 0
	v_bfi_b32 v158, s2, v2, v0
	s_movk_i32 s2, 0x2040
	s_cselect_b64 s[24:25], -1, 0
	s_cmp_eq_u32 s66, 1
	v_cmp_gt_i32_e64 s[4:5], s2, v0
	s_cselect_b64 s[26:27], -1, 0
	s_cmp_eq_u32 s66, 2
	v_writelane_b32 v255, s4, 16
	v_ashrrev_i32_e32 v4, 3, v0
	s_cselect_b64 s[28:29], -1, 0
	s_cmp_eq_u32 s66, 3
	v_readlane_b32 s16, v254, 33
	v_writelane_b32 v255, s5, 17
	s_movk_i32 s4, 0x100
	v_lshlrev_b32_e32 v6, 6, v0
	v_and_b32_e32 v124, -8, v4
	s_movk_i32 s8, 0x88
	s_cselect_b64 s[44:45], -1, 0
	v_readlane_b32 s17, v254, 34
	s_add_u32 s12, s16, s12
	v_lshlrev_b32_e32 v176, 7, v1
	v_lshrrev_b32_e32 v123, 5, v1
	v_and_b32_e32 v156, 31, v0
	v_cmp_gt_i32_e64 s[4:5], s4, v0
	v_cmp_gt_i32_e64 s[6:7], 4, v0
	v_lshlrev_b32_e32 v120, 3, v0
	v_lshlrev_b32_e32 v5, 4, v0
	v_and_b32_e32 v122, 0xfc0, v6
	v_ashrrev_i32_e32 v125, 31, v124
	v_mul_lo_u32 v165, v124, s8
	v_lshlrev_b32_e32 v166, 1, v1
	v_cmp_gt_u32_e64 s[8:9], 32, v1
	v_and_b32_e32 v6, 7, v0
	v_lshlrev_b32_e32 v8, 1, v0
	v_add_u32_e32 v201, 0xfffffe00, v0
	s_addc_u32 s13, s17, s13
	v_lshl_add_u64 v[0:1], s[0:1], 0, v[176:177]
	s_lshr_b32 s0, s14, 5
	s_movk_i32 s15, 0x204
	v_lshl_add_u64 v[0:1], v[124:125], 1, v[0:1]
	s_mulk_i32 s0, 0x4080
	v_readlane_b32 s10, v254, 41
	v_mul_lo_u32 v161, v4, s43
	v_cvt_f32_i32_e32 v164, v158
	v_mul_lo_u32 v7, v4, s15
	v_and_b32_e32 v8, 12, v8
	v_lshlrev_b32_e32 v4, 4, v4
	v_lshl_add_u64 v[128:129], s[16:17], 0, v[0:1]
	v_mov_b32_e32 v0, s0
	v_readlane_b32 s11, v254, 42
	v_and_b32_e32 v162, 0x70, v5
	v_add3_u32 v170, s10, v4, v8
	v_and_b32_e32 v171, 16, v5
	v_lshlrev_b32_e32 v5, 4, v158
	v_lshlrev_b32_e32 v4, 2, v123
	v_readlane_b32 s31, v254, 43
	v_mad_u32_u24 v0, v156, s15, v0
	v_lshlrev_b32_e32 v2, 3, v123
	v_add_u32_e32 v159, s10, v3
	v_add_u32_e32 v160, s11, v3
	v_ashrrev_i32_e32 v121, 31, v120
	v_lshlrev_b32_e32 v168, 4, v6
	v_add_u32_e32 v169, s11, v8
	v_cmp_eq_u32_e64 s[10:11], 0, v6
	v_lshlrev_b32_e32 v6, 6, v6
	v_add3_u32 v202, v0, v4, s31
	v_add_u32_e32 v0, 0, v5
	v_readlane_b32 s41, v253, 0
	v_add3_u32 v163, 0, v161, v162
	v_add3_u32 v167, 0, v165, v166
	v_add_u32_e32 v172, 1, v158
	v_add3_u32 v173, 0, v7, v6
	v_or_b32_e32 v174, 1, v168
	v_or_b32_e32 v175, 2, v168
	v_or_b32_e32 v178, 3, v168
	v_or_b32_e32 v188, 4, v168
	v_or_b32_e32 v189, 5, v168
	v_or_b32_e32 v190, 6, v168
	v_or_b32_e32 v191, 7, v168
	v_or_b32_e32 v192, 8, v168
	v_or_b32_e32 v193, 9, v168
	v_or_b32_e32 v194, 10, v168
	v_or_b32_e32 v195, 11, v168
	v_or_b32_e32 v196, 12, v168
	v_or_b32_e32 v197, 13, v168
	v_or_b32_e32 v198, 14, v168
	v_or_b32_e32 v199, 15, v168
	v_add_u32_e32 v200, s31, v3
	v_lshl_add_u64 v[126:127], v[120:121], 1, s[12:13]
	v_lshlrev_b32_e32 v176, 1, v2
	s_xor_b64 s[50:51], s[10:11], -1
	v_add_u32_e32 v203, 0x11100, v0
	v_lshlrev_b32_e32 v130, 1, v4
	s_mov_b32 s40, s41
	s_branch .LBB0_1183

.LBB0_1317:
	s_mov_b64 s[0:1], 0x80000
	s_setprio 0
	s_getreg_b32 s6, hwreg(HW_REG_XCC_ID, 0, 4)
	s_waitcnt vmcnt(0)
	s_barrier
	s_getreg_b32 s2, hwreg(HW_REG_HW_ID, 0, 6)
	s_and_b32 s2, s2, 63
	s_lshl_b32 s2, s2, 2
	s_add_i32 s2, s2, 0
	s_add_i32 s2, s2, 0x22ef0
	v_mov_b32_e32 v0, s2
	ds_read_b32 v0, v0
	s_waitcnt lgkmcnt(0)
	v_readfirstlane_b32 s2, v0
	v_mov_b32_e32 v0, v177
	s_nop 0
	v_mbcnt_lo_u32_b32 v0, -1, v0
	v_mbcnt_hi_u32_b32 v0, -1, v0
	v_lshl_add_u32 v0, s2, 6, v0
	s_nop 0
	v_cmp_eq_u32_e32 vcc, 0, v0
	s_and_saveexec_b64 s[2:3], vcc
	v_readlane_b32 s24, v254, 49
	v_readlane_b32 s25, v254, 50
	s_movk_i32 s22, 0x3fff
	s_cbranch_execz .LBB0_1369
	v_readlane_b32 s4, v254, 37
	s_waitcnt vmcnt(0) expcnt(0) lgkmcnt(0)
	s_nop 0
	v_mov_b32_e32 v0, s4
	ds_read_b32 v2, v0
	s_add_u32 s4, s66, s0
	v_readlane_b32 s0, v254, 38
	s_addc_u32 s5, s67, s1
	s_and_b32 s18, s6, 15
	v_mov_b32_e32 v0, s0
	ds_read_b32 v0, v0
	s_waitcnt lgkmcnt(1)
	v_cmp_ne_u32_e32 vcc, 0, v2
	s_cbranch_vccnz .LBB0_1333
	s_add_u32 s0, s4, 0x1000
	s_addc_u32 s1, s5, 0
	s_add_u32 s6, s4, 0x1100
	s_addc_u32 s7, s5, 0
	s_add_u32 s8, s4, 0x1200
	s_addc_u32 s9, s5, 0
	s_add_u32 s10, s4, 0x1300
	s_addc_u32 s11, s5, 0
	s_mov_b32 s19, 1
	s_branch .LBB0_1321
